# G1 batch rows: single v_dot2c accumulation chain per table row (no second accumulator, s_nop, final add), odd vmcnt waits dropped
# speedup vs baseline: 1.0524x; 1.0093x over previous
.LBB0_1026:
	s_waitcnt vmcnt(30)
	v_cvt_scalef32_pk32_f16_fp6 v[0:15], v[106:111], 1.0
	v_mov_b32_e32 v106, 0
	v_dot2c_f32_f16_e32 v106, v0, v166
	v_dot2c_f32_f16_e32 v106, v1, v167
	v_dot2c_f32_f16_e32 v106, v2, v168
	v_dot2c_f32_f16_e32 v106, v3, v169
	v_dot2c_f32_f16_e32 v106, v4, v170
	v_dot2c_f32_f16_e32 v106, v5, v171
	v_dot2c_f32_f16_e32 v106, v6, v172
	v_dot2c_f32_f16_e32 v106, v7, v173
	v_dot2c_f32_f16_e32 v106, v8, v174
	v_dot2c_f32_f16_e32 v106, v9, v175
	v_dot2c_f32_f16_e32 v106, v10, v177
	v_dot2c_f32_f16_e32 v106, v11, v178
	v_dot2c_f32_f16_e32 v106, v12, v179
	v_dot2c_f32_f16_e32 v106, v13, v180
	v_dot2c_f32_f16_e32 v106, v14, v181
	v_dot2c_f32_f16_e32 v106, v15, v182
	s_waitcnt vmcnt(28)
	v_cvt_scalef32_pk32_f16_fp6 v[0:15], v[100:105], 1.0
	v_mov_b32_e32 v100, 0
	v_dot2c_f32_f16_e32 v100, v0, v166
	v_dot2c_f32_f16_e32 v100, v1, v167
	v_dot2c_f32_f16_e32 v100, v2, v168
	v_dot2c_f32_f16_e32 v100, v3, v169
	v_dot2c_f32_f16_e32 v100, v4, v170
	v_dot2c_f32_f16_e32 v100, v5, v171
	v_dot2c_f32_f16_e32 v100, v6, v172
	v_dot2c_f32_f16_e32 v100, v7, v173
	v_dot2c_f32_f16_e32 v100, v8, v174
	v_dot2c_f32_f16_e32 v100, v9, v175
	v_dot2c_f32_f16_e32 v100, v10, v177
	v_dot2c_f32_f16_e32 v100, v11, v178
	v_dot2c_f32_f16_e32 v100, v12, v179
	v_dot2c_f32_f16_e32 v100, v13, v180
	v_dot2c_f32_f16_e32 v100, v14, v181
	v_dot2c_f32_f16_e32 v100, v15, v182
	s_waitcnt vmcnt(26)
	v_cvt_scalef32_pk32_f16_fp6 v[0:15], v[94:99], 1.0
	v_mov_b32_e32 v94, 0
	v_dot2c_f32_f16_e32 v94, v0, v166
	v_dot2c_f32_f16_e32 v94, v1, v167
	v_dot2c_f32_f16_e32 v94, v2, v168
	v_dot2c_f32_f16_e32 v94, v3, v169
	v_dot2c_f32_f16_e32 v94, v4, v170
	v_dot2c_f32_f16_e32 v94, v5, v171
	v_dot2c_f32_f16_e32 v94, v6, v172
	v_dot2c_f32_f16_e32 v94, v7, v173
	v_dot2c_f32_f16_e32 v94, v8, v174
	v_dot2c_f32_f16_e32 v94, v9, v175
	v_dot2c_f32_f16_e32 v94, v10, v177
	v_dot2c_f32_f16_e32 v94, v11, v178
	v_dot2c_f32_f16_e32 v94, v12, v179
	v_dot2c_f32_f16_e32 v94, v13, v180
	v_dot2c_f32_f16_e32 v94, v14, v181
	v_dot2c_f32_f16_e32 v94, v15, v182
	s_waitcnt vmcnt(24)
	v_cvt_scalef32_pk32_f16_fp6 v[0:15], v[88:93], 1.0
	v_mov_b32_e32 v88, 0
	v_dot2c_f32_f16_e32 v88, v0, v166
	v_dot2c_f32_f16_e32 v88, v1, v167
	v_dot2c_f32_f16_e32 v88, v2, v168
	v_dot2c_f32_f16_e32 v88, v3, v169
	v_dot2c_f32_f16_e32 v88, v4, v170
	v_dot2c_f32_f16_e32 v88, v5, v171
	v_dot2c_f32_f16_e32 v88, v6, v172
	v_dot2c_f32_f16_e32 v88, v7, v173
	v_dot2c_f32_f16_e32 v88, v8, v174
	v_dot2c_f32_f16_e32 v88, v9, v175
	v_dot2c_f32_f16_e32 v88, v10, v177
	v_dot2c_f32_f16_e32 v88, v11, v178
	v_dot2c_f32_f16_e32 v88, v12, v179
	v_dot2c_f32_f16_e32 v88, v13, v180
	v_dot2c_f32_f16_e32 v88, v14, v181
	v_dot2c_f32_f16_e32 v88, v15, v182
	s_waitcnt vmcnt(22)
	v_cvt_scalef32_pk32_f16_fp6 v[0:15], v[82:87], 1.0
	v_mov_b32_e32 v82, 0
	v_dot2c_f32_f16_e32 v82, v0, v166
	v_dot2c_f32_f16_e32 v82, v1, v167
	v_dot2c_f32_f16_e32 v82, v2, v168
	v_dot2c_f32_f16_e32 v82, v3, v169
	v_dot2c_f32_f16_e32 v82, v4, v170
	v_dot2c_f32_f16_e32 v82, v5, v171
	v_dot2c_f32_f16_e32 v82, v6, v172
	v_dot2c_f32_f16_e32 v82, v7, v173
	v_dot2c_f32_f16_e32 v82, v8, v174
	v_dot2c_f32_f16_e32 v82, v9, v175
	v_dot2c_f32_f16_e32 v82, v10, v177
	v_dot2c_f32_f16_e32 v82, v11, v178
	v_dot2c_f32_f16_e32 v82, v12, v179
	v_dot2c_f32_f16_e32 v82, v13, v180
	v_dot2c_f32_f16_e32 v82, v14, v181
	v_dot2c_f32_f16_e32 v82, v15, v182
	s_waitcnt vmcnt(20)
	v_cvt_scalef32_pk32_f16_fp6 v[0:15], v[76:81], 1.0
	v_mov_b32_e32 v76, 0
	v_dot2c_f32_f16_e32 v76, v0, v166
	v_dot2c_f32_f16_e32 v76, v1, v167
	v_dot2c_f32_f16_e32 v76, v2, v168
	v_dot2c_f32_f16_e32 v76, v3, v169
	v_dot2c_f32_f16_e32 v76, v4, v170
	v_dot2c_f32_f16_e32 v76, v5, v171
	v_dot2c_f32_f16_e32 v76, v6, v172
	v_dot2c_f32_f16_e32 v76, v7, v173
	v_dot2c_f32_f16_e32 v76, v8, v174
	v_dot2c_f32_f16_e32 v76, v9, v175
	v_dot2c_f32_f16_e32 v76, v10, v177
	v_dot2c_f32_f16_e32 v76, v11, v178
	v_dot2c_f32_f16_e32 v76, v12, v179
	v_dot2c_f32_f16_e32 v76, v13, v180
	v_dot2c_f32_f16_e32 v76, v14, v181
	v_dot2c_f32_f16_e32 v76, v15, v182
	s_waitcnt vmcnt(18)
	v_cvt_scalef32_pk32_f16_fp6 v[0:15], v[70:75], 1.0
	v_mov_b32_e32 v70, 0
	v_dot2c_f32_f16_e32 v70, v0, v166
	v_dot2c_f32_f16_e32 v70, v1, v167
	v_dot2c_f32_f16_e32 v70, v2, v168
	v_dot2c_f32_f16_e32 v70, v3, v169
	v_dot2c_f32_f16_e32 v70, v4, v170
	v_dot2c_f32_f16_e32 v70, v5, v171
	v_dot2c_f32_f16_e32 v70, v6, v172
	v_dot2c_f32_f16_e32 v70, v7, v173
	v_dot2c_f32_f16_e32 v70, v8, v174
	v_dot2c_f32_f16_e32 v70, v9, v175
	v_dot2c_f32_f16_e32 v70, v10, v177
	v_dot2c_f32_f16_e32 v70, v11, v178
	v_dot2c_f32_f16_e32 v70, v12, v179
	v_dot2c_f32_f16_e32 v70, v13, v180
	v_dot2c_f32_f16_e32 v70, v14, v181
	v_dot2c_f32_f16_e32 v70, v15, v182
	s_waitcnt vmcnt(16)
	v_cvt_scalef32_pk32_f16_fp6 v[0:15], v[64:69], 1.0
	v_mov_b32_e32 v64, 0
	v_dot2c_f32_f16_e32 v64, v0, v166
	v_dot2c_f32_f16_e32 v64, v1, v167
	v_dot2c_f32_f16_e32 v64, v2, v168
	v_dot2c_f32_f16_e32 v64, v3, v169
	v_dot2c_f32_f16_e32 v64, v4, v170
	v_dot2c_f32_f16_e32 v64, v5, v171
	v_dot2c_f32_f16_e32 v64, v6, v172
	v_dot2c_f32_f16_e32 v64, v7, v173
	v_dot2c_f32_f16_e32 v64, v8, v174
	v_dot2c_f32_f16_e32 v64, v9, v175
	v_dot2c_f32_f16_e32 v64, v10, v177
	v_dot2c_f32_f16_e32 v64, v11, v178
	v_dot2c_f32_f16_e32 v64, v12, v179
	v_dot2c_f32_f16_e32 v64, v13, v180
	v_dot2c_f32_f16_e32 v64, v14, v181
	v_dot2c_f32_f16_e32 v64, v15, v182
	s_waitcnt vmcnt(14)
	v_cvt_scalef32_pk32_f16_fp6 v[0:15], v[58:63], 1.0
	v_mov_b32_e32 v58, 0
	v_dot2c_f32_f16_e32 v58, v0, v166
	v_dot2c_f32_f16_e32 v58, v1, v167
	v_dot2c_f32_f16_e32 v58, v2, v168
	v_dot2c_f32_f16_e32 v58, v3, v169
	v_dot2c_f32_f16_e32 v58, v4, v170
	v_dot2c_f32_f16_e32 v58, v5, v171
	v_dot2c_f32_f16_e32 v58, v6, v172
	v_dot2c_f32_f16_e32 v58, v7, v173
	v_dot2c_f32_f16_e32 v58, v8, v174
	v_dot2c_f32_f16_e32 v58, v9, v175
	v_dot2c_f32_f16_e32 v58, v10, v177
	v_dot2c_f32_f16_e32 v58, v11, v178
	v_dot2c_f32_f16_e32 v58, v12, v179
	v_dot2c_f32_f16_e32 v58, v13, v180
	v_dot2c_f32_f16_e32 v58, v14, v181
	v_dot2c_f32_f16_e32 v58, v15, v182
	s_waitcnt vmcnt(12)
	v_cvt_scalef32_pk32_f16_fp6 v[0:15], v[52:57], 1.0
	v_mov_b32_e32 v52, 0
	v_permlane16_swap_b32_e32 v106, v58
	v_dot2c_f32_f16_e32 v52, v0, v166
	v_dot2c_f32_f16_e32 v52, v1, v167
	v_dot2c_f32_f16_e32 v52, v2, v168
	v_dot2c_f32_f16_e32 v52, v3, v169
	v_dot2c_f32_f16_e32 v52, v4, v170
	v_dot2c_f32_f16_e32 v52, v5, v171
	v_dot2c_f32_f16_e32 v52, v6, v172
	v_dot2c_f32_f16_e32 v52, v7, v173
	v_dot2c_f32_f16_e32 v52, v8, v174
	v_dot2c_f32_f16_e32 v52, v9, v175
	v_dot2c_f32_f16_e32 v52, v10, v177
	v_dot2c_f32_f16_e32 v52, v11, v178
	v_dot2c_f32_f16_e32 v52, v12, v179
	v_dot2c_f32_f16_e32 v52, v13, v180
	v_dot2c_f32_f16_e32 v52, v14, v181
	v_dot2c_f32_f16_e32 v52, v15, v182
	s_waitcnt vmcnt(10)
	v_cvt_scalef32_pk32_f16_fp6 v[0:15], v[46:51], 1.0
	v_mov_b32_e32 v46, 0
	v_permlane16_swap_b32_e32 v100, v52
	v_dot2c_f32_f16_e32 v46, v0, v166
	v_dot2c_f32_f16_e32 v46, v1, v167
	v_dot2c_f32_f16_e32 v46, v2, v168
	v_dot2c_f32_f16_e32 v46, v3, v169
	v_dot2c_f32_f16_e32 v46, v4, v170
	v_dot2c_f32_f16_e32 v46, v5, v171
	v_dot2c_f32_f16_e32 v46, v6, v172
	v_dot2c_f32_f16_e32 v46, v7, v173
	v_dot2c_f32_f16_e32 v46, v8, v174
	v_dot2c_f32_f16_e32 v46, v9, v175
	v_dot2c_f32_f16_e32 v46, v10, v177
	v_dot2c_f32_f16_e32 v46, v11, v178
	v_dot2c_f32_f16_e32 v46, v12, v179
	v_dot2c_f32_f16_e32 v46, v13, v180
	v_dot2c_f32_f16_e32 v46, v14, v181
	v_dot2c_f32_f16_e32 v46, v15, v182
	s_waitcnt vmcnt(8)
	v_cvt_scalef32_pk32_f16_fp6 v[0:15], v[40:45], 1.0
	v_mov_b32_e32 v40, 0
	v_permlane16_swap_b32_e32 v94, v46
	v_dot2c_f32_f16_e32 v40, v0, v166
	v_dot2c_f32_f16_e32 v40, v1, v167
	v_dot2c_f32_f16_e32 v40, v2, v168
	v_dot2c_f32_f16_e32 v40, v3, v169
	v_dot2c_f32_f16_e32 v40, v4, v170
	v_dot2c_f32_f16_e32 v40, v5, v171
	v_dot2c_f32_f16_e32 v40, v6, v172
	v_dot2c_f32_f16_e32 v40, v7, v173
	v_dot2c_f32_f16_e32 v40, v8, v174
	v_dot2c_f32_f16_e32 v40, v9, v175
	v_dot2c_f32_f16_e32 v40, v10, v177
	v_dot2c_f32_f16_e32 v40, v11, v178
	v_dot2c_f32_f16_e32 v40, v12, v179
	v_dot2c_f32_f16_e32 v40, v13, v180
	v_dot2c_f32_f16_e32 v40, v14, v181
	v_dot2c_f32_f16_e32 v40, v15, v182
	s_waitcnt vmcnt(6)
	v_cvt_scalef32_pk32_f16_fp6 v[0:15], v[34:39], 1.0
	v_mov_b32_e32 v34, 0
	v_permlane16_swap_b32_e32 v88, v40
	v_dot2c_f32_f16_e32 v34, v0, v166
	v_dot2c_f32_f16_e32 v34, v1, v167
	v_dot2c_f32_f16_e32 v34, v2, v168
	v_dot2c_f32_f16_e32 v34, v3, v169
	v_dot2c_f32_f16_e32 v34, v4, v170
	v_dot2c_f32_f16_e32 v34, v5, v171
	v_dot2c_f32_f16_e32 v34, v6, v172
	v_dot2c_f32_f16_e32 v34, v7, v173
	v_dot2c_f32_f16_e32 v34, v8, v174
	v_dot2c_f32_f16_e32 v34, v9, v175
	v_dot2c_f32_f16_e32 v34, v10, v177
	v_dot2c_f32_f16_e32 v34, v11, v178
	v_dot2c_f32_f16_e32 v34, v12, v179
	v_dot2c_f32_f16_e32 v34, v13, v180
	v_dot2c_f32_f16_e32 v34, v14, v181
	v_dot2c_f32_f16_e32 v34, v15, v182
	s_waitcnt vmcnt(4)
	v_cvt_scalef32_pk32_f16_fp6 v[0:15], v[28:33], 1.0
	v_mov_b32_e32 v28, 0
	v_permlane16_swap_b32_e32 v82, v34
	v_dot2c_f32_f16_e32 v28, v0, v166
	v_dot2c_f32_f16_e32 v28, v1, v167
	v_dot2c_f32_f16_e32 v28, v2, v168
	v_dot2c_f32_f16_e32 v28, v3, v169
	v_dot2c_f32_f16_e32 v28, v4, v170
	v_dot2c_f32_f16_e32 v28, v5, v171
	v_dot2c_f32_f16_e32 v28, v6, v172
	v_dot2c_f32_f16_e32 v28, v7, v173
	v_dot2c_f32_f16_e32 v28, v8, v174
	v_dot2c_f32_f16_e32 v28, v9, v175
	v_dot2c_f32_f16_e32 v28, v10, v177
	v_dot2c_f32_f16_e32 v28, v11, v178
	v_dot2c_f32_f16_e32 v28, v12, v179
	v_dot2c_f32_f16_e32 v28, v13, v180
	v_dot2c_f32_f16_e32 v28, v14, v181
	v_dot2c_f32_f16_e32 v28, v15, v182
	s_waitcnt vmcnt(2)
	v_cvt_scalef32_pk32_f16_fp6 v[0:15], v[22:27], 1.0
	v_mov_b32_e32 v22, 0
	v_permlane16_swap_b32_e32 v76, v28
	v_dot2c_f32_f16_e32 v22, v0, v166
	v_dot2c_f32_f16_e32 v22, v1, v167
	v_dot2c_f32_f16_e32 v22, v2, v168
	v_dot2c_f32_f16_e32 v22, v3, v169
	v_dot2c_f32_f16_e32 v22, v4, v170
	v_dot2c_f32_f16_e32 v22, v5, v171
	v_dot2c_f32_f16_e32 v22, v6, v172
	v_dot2c_f32_f16_e32 v22, v7, v173
	v_dot2c_f32_f16_e32 v22, v8, v174
	v_dot2c_f32_f16_e32 v22, v9, v175
	v_dot2c_f32_f16_e32 v22, v10, v177
	v_dot2c_f32_f16_e32 v22, v11, v178
	v_dot2c_f32_f16_e32 v22, v12, v179
	v_dot2c_f32_f16_e32 v22, v13, v180
	v_dot2c_f32_f16_e32 v22, v14, v181
	v_dot2c_f32_f16_e32 v22, v15, v182
	s_waitcnt vmcnt(0)
	v_cvt_scalef32_pk32_f16_fp6 v[0:15], v[16:21], 1.0
	v_mov_b32_e32 v16, 0
	v_permlane16_swap_b32_e32 v70, v22
	v_dot2c_f32_f16_e32 v16, v0, v166
	v_dot2c_f32_f16_e32 v16, v1, v167
	v_dot2c_f32_f16_e32 v16, v2, v168
	v_dot2c_f32_f16_e32 v16, v3, v169
	v_dot2c_f32_f16_e32 v16, v4, v170
	v_dot2c_f32_f16_e32 v16, v5, v171
	v_dot2c_f32_f16_e32 v16, v6, v172
	v_dot2c_f32_f16_e32 v16, v7, v173
	v_dot2c_f32_f16_e32 v16, v8, v174
	v_dot2c_f32_f16_e32 v16, v9, v175
	v_dot2c_f32_f16_e32 v16, v10, v177
	v_dot2c_f32_f16_e32 v16, v11, v178
	v_dot2c_f32_f16_e32 v16, v12, v179
	v_dot2c_f32_f16_e32 v16, v13, v180
	v_dot2c_f32_f16_e32 v16, v14, v181
	v_dot2c_f32_f16_e32 v16, v15, v182
	v_add_f32_e32 v2, v100, v52
	v_add_f32_e32 v5, v82, v34
	v_add_f32_e32 v6, v76, v28
	v_mov_b32_e32 v0, v16
	v_add_f32_e32 v1, v106, v58
	v_add_f32_e32 v3, v94, v46
	v_add_f32_e32 v7, v70, v22
	v_permlane16_swap_b32_e32 v64, v0
	v_cndmask_b32_e64 v8, v1, v5, s[6:7]
	v_cndmask_b32_e64 v1, v5, v1, s[6:7]
	v_cndmask_b32_e64 v5, v2, v6, s[6:7]
	v_cndmask_b32_e64 v2, v6, v2, s[6:7]
	v_add_f32_e32 v4, v88, v40
	v_add_f32_e32 v0, v64, v0
	v_add_f32_dpp v2, v5, v2 row_ror:8 row_mask:0xf bank_mask:0xf bound_ctrl:1
	v_cndmask_b32_e64 v5, v3, v7, s[6:7]
	v_cndmask_b32_e64 v3, v7, v3, s[6:7]
	v_add_f32_dpp v1, v8, v1 row_ror:8 row_mask:0xf bank_mask:0xf bound_ctrl:1
	s_nop 0
	v_add_f32_dpp v3, v5, v3 row_ror:8 row_mask:0xf bank_mask:0xf bound_ctrl:1
	v_cndmask_b32_e64 v5, v4, v0, s[6:7]
	v_cndmask_b32_e64 v0, v0, v4, s[6:7]
	v_xor_b32_e32 v4, 4, v130
	s_nop 0
	v_add_f32_dpp v0, v5, v0 row_ror:8 row_mask:0xf bank_mask:0xf bound_ctrl:1
	v_and_b32_e32 v5, 64, v130
	v_add_u32_e32 v5, 64, v5
	v_cmp_lt_i32_e32 vcc, v4, v5
	v_cndmask_b32_e64 v5, v1, v3, s[8:9]
	v_cndmask_b32_e64 v6, v2, v0, s[8:9]
	v_cndmask_b32_e32 v4, v130, v4, vcc
	v_lshlrev_b32_e32 v4, 2, v4
	ds_bpermute_b32 v5, v4, v5
	ds_bpermute_b32 v4, v4, v6
	v_cndmask_b32_e64 v1, v3, v1, s[8:9]
	v_cndmask_b32_e64 v0, v0, v2, s[8:9]
	s_waitcnt lgkmcnt(1)
	v_add_f32_e32 v1, v1, v5
	s_waitcnt lgkmcnt(0)
	v_add_f32_e32 v0, v0, v4
	v_cndmask_b32_e64 v2, v1, v0, s[10:11]
	v_cndmask_b32_e64 v0, v0, v1, s[10:11]
	s_nop 1
	v_add_f32_dpp v1, v2, v0 quad_perm:[2,3,0,1] row_mask:0xf bank_mask:0xf bound_ctrl:1
	s_nop 1
	v_mov_b32_dpp v2, v1 quad_perm:[1,0,3,2] row_mask:0xf bank_mask:0xf bound_ctrl:1
	s_and_saveexec_b64 s[42:43], s[12:13]
	s_cbranch_execz .LBB0_1014
	v_add_u32_e32 v0, v183, v129
	ds_read_b32 v3, v0 offset:1536
	v_add_f32_e32 v1, v1, v2
	s_waitcnt lgkmcnt(0)
	v_mul_f32_e32 v1, v1, v3
	v_mul_f32_e32 v2, 0x3f3504f3, v1
	v_cmp_nlt_f32_e64 s[44:45], |v2|, 1.0
	s_and_saveexec_b64 s[64:65], s[44:45]
	s_xor_b64 s[44:45], exec, s[64:65]
	s_cbranch_execz .LBB0_1029
	v_fma_f32 v3, |v2|, s52, v139
	v_fma_f32 v3, |v2|, v3, s53
	v_fma_f32 v3, |v2|, v3, s54
	v_fma_f32 v3, |v2|, v3, s55
	v_fma_f32 v3, |v2|, v3, s56
	v_fma_f32 v3, |v2|, v3, s57
	v_fma_f32 v3, |v2|, v3, |v2|
	v_mul_f32_e32 v4, 0xbfb8aa3b, v3
	v_fma_f32 v5, v3, s58, -v4
	v_rndne_f32_e32 v6, v4
	v_fmac_f32_e32 v5, 0xb2a5705f, v3
	v_sub_f32_e32 v4, v4, v6
	v_add_f32_e32 v4, v4, v5
	v_cvt_i32_f32_e32 v5, v6
	v_exp_f32_e32 v4, v4
	v_cmp_nlt_f32_e32 vcc, s59, v3
	v_ldexp_f32 v4, v4, v5
	s_nop 0
	v_cndmask_b32_e32 v4, 0, v4, vcc
	v_cmp_ngt_f32_e32 vcc, s60, v3
	s_nop 1
	v_cndmask_b32_e32 v3, v140, v4, vcc
	v_sub_f32_e32 v3, 1.0, v3
